# scan: bf16 pack of the state moved from the head of the O part (after the barrier) to the end of the previous half-step
# speedup vs baseline: 1.0001x; 1.0001x over previous
; #define LAS __attribute__((address_space(3)))
; __device__ __forceinline__ unsigned pk2(float lo, float hi) { const f32x2_t v = {lo, hi}; const bf16x2_t b = __builtin_convertvector(v, bf16x2_t); return __builtin_bit_cast(unsigned, b); }
; __device__ __forceinline__ bf16x8 cat8(const s16x4 a, const s16x4 b) { return __builtin_shufflevector(a, b, 0, 1, 2, 3, 4, 5, 6, 7); }
; __device__ __forceinline__ void hgrn_scan(const Params& p, LAS unsigned char* lds, int chain) {
;     ...
;             bf16* orow = O + (long)hg_row(dir, b, 64 * c) * WA;
; #pragma unroll
;             for (int I = 0; I < 4; ++I) {
;                 f32x4 o = (f32x4){0.f, 0.f, 0.f, 0.f};
; #pragma unroll
;                 for (int ks = 0; ks < 4; ++ks) {
;                     const LAS unsigned char* ap = bb + SB_QD + (32 * ks + 4 * g + qq) * HP + (16 * I + 4 * pp) * 2;
;                     o = __builtin_amdgcn_mfma_f32_16x16x32_bf16(sb[ks], cat8(lds_tr(ap), lds_tr(ap + 16 * HP)), o, 0, 0, 0);
;                 }
; #pragma unroll
;                 for (int sp = 0; sp < 2; ++sp) {
;                     if (2 * sp > I) break;
;                     const LAS unsigned char* pr = bb + SB_P + (16 * I + li) * PP + (32 * sp + 4 * g) * 2;
;                     const u32x2 lo = *(const LAS u32x2*)pr; u32x2 hi = (u32x2){0u, 0u};
;                     if (2 * sp + 1 <= I) hi = *(const LAS u32x2*)(pr + 32);
;                     o = __builtin_amdgcn_mfma_f32_16x16x32_bf16(vf[sp], cat8u(lo, hi), o, 0, 0, 0);
;                 }
;                 { u32x2 w; w.x = pk2(o.x, o.y); w.y = pk2(o.z, o.w); *(u32x2*)(orow + (long)(16 * I + li) * ost) = w; }
;             }
.LBB0_410:
	s_andn2_b64 vcc, exec, s[18:19]
	s_cbranch_vccnz .LBB0_412
	v_add_u32_e32 v165, v139, v141
	ds_read_b64_tr_b16 v[176:177], v165 offset:2560
	ds_read_b64_tr_b16 v[174:175], v165
	ds_read_b64_tr_b16 v[178:179], v165 offset:32
	ds_read_b64_tr_b16 v[182:183], v165 offset:64
	ds_read_b64_tr_b16 v[186:187], v165 offset:96
	ds_read_b64_tr_b16 v[180:181], v165 offset:2592
	ds_read_b64_tr_b16 v[184:185], v165 offset:2624
	ds_read_b64_tr_b16 v[188:189], v165 offset:2656
	s_waitcnt lgkmcnt(6)
	v_mfma_f32_16x16x32_bf16 v[174:177], v[104:107], v[174:177], 0
	s_waitcnt lgkmcnt(2)
	v_mfma_f32_16x16x32_bf16 v[178:181], v[104:107], v[178:181], 0
	ds_read_b64_tr_b16 v[192:193], v165 offset:7680
	ds_read_b64_tr_b16 v[190:191], v165 offset:5120
	ds_read_b64_tr_b16 v[194:195], v165 offset:5152
	ds_read_b64_tr_b16 v[198:199], v165 offset:5184
	ds_read_b64_tr_b16 v[202:203], v165 offset:5216
	ds_read_b64_tr_b16 v[196:197], v165 offset:7712
	ds_read_b64_tr_b16 v[200:201], v165 offset:7744
	ds_read_b64_tr_b16 v[204:205], v165 offset:7776
	s_waitcnt lgkmcnt(6)
	v_mfma_f32_16x16x32_bf16 v[174:177], v[108:111], v[190:193], v[174:177]
	ds_read_b64_tr_b16 v[192:193], v165 offset:12800
	ds_read_b64_tr_b16 v[190:191], v165 offset:10240
	ds_read_b64_tr_b16 v[206:207], v165 offset:10272
	ds_read_b64_tr_b16 v[210:211], v165 offset:10304
	ds_read_b64_tr_b16 v[214:215], v165 offset:10336
	ds_read_b64_tr_b16 v[208:209], v165 offset:12832
	ds_read_b64_tr_b16 v[212:213], v165 offset:12864
	ds_read_b64_tr_b16 v[216:217], v165 offset:12896
	s_waitcnt lgkmcnt(10)
	v_mfma_f32_16x16x32_bf16 v[178:181], v[108:111], v[194:197], v[178:181]
	v_add_u32_e32 v234, v140, v142
	v_mov_b32_e32 v220, v115
	v_mfma_f32_16x16x32_bf16 v[182:185], v[104:107], v[182:185], 0
	v_mov_b32_e32 v221, v115
	s_and_b64 s[18:19], s[6:7], exec
	s_cselect_b32 s12, s22, s20
	s_waitcnt lgkmcnt(6)
	v_mfma_f32_16x16x32_bf16 v[174:177], v[166:169], v[190:193], v[174:177]
	ds_read_b64_tr_b16 v[192:193], v165 offset:17920
	ds_read_b64 v[218:219], v234 offset:40960
	ds_read_b64_tr_b16 v[190:191], v165 offset:15360
	ds_read_b64_tr_b16 v[222:223], v165 offset:15392
	ds_read_b64_tr_b16 v[226:227], v165 offset:15424
	ds_read_b64_tr_b16 v[230:231], v165 offset:15456
	ds_read_b64_tr_b16 v[224:225], v165 offset:17952
	ds_read_b64_tr_b16 v[228:229], v165 offset:17984
	ds_read_b64_tr_b16 v[232:233], v165 offset:18016
	v_add_u32_e32 v165, 0xa800, v234
	s_waitcnt lgkmcnt(11)
	v_mfma_f32_16x16x32_bf16 v[178:181], v[166:169], v[206:209], v[178:181]
	s_lshl_b64 s[18:19], s[12:13], 11
	v_mfma_f32_16x16x32_bf16 v[182:185], v[108:111], v[198:201], v[182:185]
	s_waitcnt lgkmcnt(6)
	v_mfma_f32_16x16x32_bf16 v[174:177], v[170:173], v[190:193], v[174:177]
	ds_read2_b64 v[192:195], v165 offset0:32 offset1:36
	v_add_u32_e32 v165, 0xb000, v234
	ds_read_b64 v[190:191], v234 offset:45632
	s_waitcnt lgkmcnt(4)
	v_mfma_f32_16x16x32_bf16 v[178:181], v[170:173], v[222:225], v[178:181]
	v_mfma_f32_16x16x32_bf16 v[182:185], v[166:169], v[210:213], v[182:185]
	v_mfma_f32_16x16x32_bf16 v[104:107], v[104:107], v[186:189], 0
	s_waitcnt lgkmcnt(1)
	v_mfma_f32_16x16x32_bf16 v[178:181], v[100:103], v[192:195], v[178:181]
	ds_read2_b64 v[192:195], v165 offset0:64 offset1:68
	v_add_u32_e32 v165, 0xb800, v234
	v_mfma_f32_16x16x32_bf16 v[182:185], v[170:173], v[226:229], v[182:185]
	v_mfma_f32_16x16x32_bf16 v[104:107], v[108:111], v[202:205], v[104:107]
	ds_read2_b64 v[108:111], v165 offset0:96 offset1:100
	s_waitcnt lgkmcnt(1)
	v_mfma_f32_16x16x32_bf16 v[182:185], v[100:103], v[192:195], v[182:185]
	v_mov_b32_e32 v192, v115
	v_mov_b32_e32 v193, v115
	v_mfma_f32_16x16x32_bf16 v[104:107], v[166:169], v[214:217], v[104:107]
	v_mfma_f32_16x16x32_bf16 v[174:177], v[100:103], v[218:221], v[174:177]
	v_mfma_f32_16x16x32_bf16 v[182:185], v[96:99], v[190:193], v[182:185]
	v_lshl_add_u64 v[190:191], v[118:119], 0, s[18:19]
	s_nop 5
	v_cvt_pk_bf16_f32 v174, v174, v175
	v_cvt_pk_bf16_f32 v175, v176, v177
	v_mfma_f32_16x16x32_bf16 v[104:107], v[170:173], v[230:233], v[104:107]
	v_lshl_add_u64 v[176:177], v[120:121], 1, v[190:191]
	global_store_dwordx2 v[176:177], v[174:175], off
	v_cvt_pk_bf16_f32 v174, v178, v179
	v_cvt_pk_bf16_f32 v175, v180, v181
	v_lshl_add_u64 v[166:167], v[122:123], 1, v[190:191]
	global_store_dwordx2 v[166:167], v[174:175], off
	ds_read2_b64 v[166:169], v165 offset0:104 offset1:108
	s_waitcnt lgkmcnt(1)
	v_mfma_f32_16x16x32_bf16 v[104:107], v[100:103], v[108:111], v[104:107]
	v_cvt_pk_bf16_f32 v170, v182, v183
	v_cvt_pk_bf16_f32 v171, v184, v185
	v_lshl_add_u64 v[108:109], v[124:125], 1, v[190:191]
	s_waitcnt lgkmcnt(0)
	v_mfma_f32_16x16x32_bf16 v[104:107], v[96:99], v[166:169], v[104:107]
	global_store_dwordx2 v[108:109], v[170:171], off
	s_nop 6
	v_cvt_pk_bf16_f32 v104, v104, v105
	v_cvt_pk_bf16_f32 v105, v106, v107
	v_lshl_add_u64 v[106:107], v[126:127], 1, v[190:191]
	global_store_dwordx2 v[106:107], v[104:105], off
; #define LAS __attribute__((address_space(3)))
; __device__ __forceinline__ void hgrn_scan(const Params& p, LAS unsigned char* lds, int chain) {
;     ...
;             for (int ks = 0; ks < 4; ++ks) sb[ks] = pack_p(S[2 * ks], S[2 * ks + 1]);
;     ...
; #pragma unroll
;         for (int blk = 0; blk < 8; ++blk) {
;             const f32x4 d4 = *(const LAS f32x4*)(bb + SB_D + (16 * blk + 4 * g) * 4);
;             f32x4 s = S[blk] * d4;
; #pragma unroll
;             for (int sp = 0; sp < 2; ++sp) {
;                 const LAS unsigned char* kp = bb + SB_KD + (16 * blk + li) * HPK + (32 * sp + 4 * g) * 2;
;                 s = __builtin_amdgcn_mfma_f32_16x16x32_bf16(cat8u(*(const LAS u32x2*)kp, *(const LAS u32x2*)(kp + 32)), vf[sp], s, 0, 0, 0);
;             }
;             S[blk] = s;
;         }
;         if (c + 1 < NCH) HS_STORE(c + 1, (uu + 1) & 1);
.LBB0_412:
	v_add_u32_e32 v165, v140, v144
	v_add_u32_e32 v174, v140, v116
	ds_read_b128 v[180:183], v174 offset:50176
	ds_read_b64 v[184:185], v165 offset:20480
	ds_read_b64 v[186:187], v165 offset:20512
	ds_read_b64 v[188:189], v165 offset:20544
	ds_read_b64 v[190:191], v165 offset:20576
	ds_read_b128 v[192:195], v174 offset:50240
	ds_read_b64 v[196:197], v165 offset:22656
	ds_read_b64 v[198:199], v165 offset:22688
	ds_read_b64 v[200:201], v165 offset:22720
	ds_read_b64 v[202:203], v165 offset:22752
	s_waitcnt lgkmcnt(10)
	ds_read_b128 v[204:207], v174 offset:50304
	ds_read_b64 v[208:209], v165 offset:24832
	ds_read_b64 v[210:211], v165 offset:24864
	ds_read_b64 v[212:213], v165 offset:24896
	ds_read_b64 v[214:215], v165 offset:24928
	s_waitcnt lgkmcnt(5)
	v_pk_mul_f32 v[76:77], v[76:77], v[180:181]
	v_pk_mul_f32 v[78:79], v[78:79], v[182:183]
	v_pk_mul_f32 v[92:93], v[92:93], v[192:193]
	v_pk_mul_f32 v[94:95], v[94:95], v[194:195]
	v_mfma_f32_16x16x32_bf16 v[76:79], v[184:187], v[100:103], v[76:79]
	s_nop 0
	v_mfma_f32_16x16x32_bf16 v[92:95], v[196:199], v[100:103], v[92:95]
	v_mfma_f32_16x16x32_bf16 v[76:79], v[188:191], v[96:99], v[76:79]
	v_mfma_f32_16x16x32_bf16 v[92:95], v[200:203], v[96:99], v[92:95]
	ds_read_b128 v[180:183], v174 offset:50368
	ds_read_b64 v[184:185], v165 offset:27008
	ds_read_b64 v[186:187], v165 offset:27040
	ds_read_b64 v[188:189], v165 offset:27072
	ds_read_b64 v[190:191], v165 offset:27104
	ds_read_b128 v[192:195], v174 offset:50432
	ds_read_b64 v[196:197], v165 offset:29184
	ds_read_b64 v[198:199], v165 offset:29216
	ds_read_b64 v[200:201], v165 offset:29248
	ds_read_b64 v[202:203], v165 offset:29280
	s_waitcnt lgkmcnt(5)
	v_pk_mul_f32 v[80:81], v[80:81], v[204:205]
	v_pk_mul_f32 v[82:83], v[82:83], v[206:207]
	v_pk_mul_f32 v[88:89], v[88:89], v[180:181]
	v_pk_mul_f32 v[90:91], v[90:91], v[182:183]
	v_mfma_f32_16x16x32_bf16 v[80:83], v[208:211], v[100:103], v[80:83]
	s_nop 0
	v_mfma_f32_16x16x32_bf16 v[88:91], v[184:187], v[100:103], v[88:91]
	v_mfma_f32_16x16x32_bf16 v[80:83], v[212:215], v[96:99], v[80:83]
	v_mfma_f32_16x16x32_bf16 v[88:91], v[188:191], v[96:99], v[88:91]
	ds_read_b128 v[204:207], v174 offset:50496
	ds_read_b64 v[208:209], v165 offset:31360
	ds_read_b64 v[210:211], v165 offset:31392
	ds_read_b64 v[212:213], v165 offset:31424
	ds_read_b64 v[214:215], v165 offset:31456
	ds_read_b128 v[180:183], v174 offset:50560
	ds_read_b64 v[184:185], v165 offset:33536
	ds_read_b64 v[186:187], v165 offset:33568
	ds_read_b64 v[188:189], v165 offset:33600
	ds_read_b64 v[190:191], v165 offset:33632
	s_waitcnt lgkmcnt(5)
	v_pk_mul_f32 v[72:73], v[72:73], v[192:193]
	v_pk_mul_f32 v[74:75], v[74:75], v[194:195]
	v_pk_mul_f32 v[84:85], v[84:85], v[204:205]
	v_pk_mul_f32 v[86:87], v[86:87], v[206:207]
	v_mfma_f32_16x16x32_bf16 v[72:75], v[196:199], v[100:103], v[72:75]
	s_nop 0
	v_mfma_f32_16x16x32_bf16 v[84:87], v[208:211], v[100:103], v[84:87]
	v_mfma_f32_16x16x32_bf16 v[72:75], v[200:203], v[96:99], v[72:75]
	v_mfma_f32_16x16x32_bf16 v[84:87], v[212:215], v[96:99], v[84:87]
	ds_read_b128 v[192:195], v174 offset:50624
	ds_read_b64 v[196:197], v165 offset:35712
	ds_read_b64 v[198:199], v165 offset:35744
	ds_read_b64 v[200:201], v165 offset:35776
	ds_read_b64 v[202:203], v165 offset:35808
	s_waitcnt lgkmcnt(0)
	v_pk_mul_f32 v[64:65], v[64:65], v[180:181]
	v_pk_mul_f32 v[66:67], v[66:67], v[182:183]
	v_pk_mul_f32 v[68:69], v[68:69], v[192:193]
	v_pk_mul_f32 v[70:71], v[70:71], v[194:195]
	v_mfma_f32_16x16x32_bf16 v[64:67], v[184:187], v[100:103], v[64:67]
	s_nop 0
	v_mfma_f32_16x16x32_bf16 v[68:71], v[196:199], v[100:103], v[68:71]
	v_mfma_f32_16x16x32_bf16 v[64:67], v[188:191], v[96:99], v[64:67]
	v_mfma_f32_16x16x32_bf16 v[68:71], v[200:203], v[96:99], v[68:71]
	v_cvt_pk_bf16_f32 v104, v76, v77
	v_cvt_pk_bf16_f32 v105, v78, v79
	v_cvt_pk_bf16_f32 v106, v92, v93
	v_cvt_pk_bf16_f32 v107, v94, v95
	v_cvt_pk_bf16_f32 v108, v80, v81
	v_cvt_pk_bf16_f32 v109, v82, v83
	v_cvt_pk_bf16_f32 v110, v88, v89
	v_cvt_pk_bf16_f32 v111, v90, v91
	v_cvt_pk_bf16_f32 v166, v72, v73
	v_cvt_pk_bf16_f32 v167, v74, v75
	v_cvt_pk_bf16_f32 v168, v84, v85
	v_cvt_pk_bf16_f32 v169, v86, v87
	v_cvt_pk_bf16_f32 v170, v64, v65
	v_cvt_pk_bf16_f32 v171, v66, v67
	v_cvt_pk_bf16_f32 v172, v68, v69
	v_cvt_pk_bf16_f32 v173, v70, v71
	s_cmp_lt_u32 s23, 3
	s_cbranch_scc1 .LBB0_414
	s_waitcnt vmcnt(6)
	ds_write_b128 v158, v[40:43]
	s_waitcnt vmcnt(5)
	ds_write_b128 v158, v[44:47] offset:10240
	s_waitcnt vmcnt(4)
	ds_write_b128 v159, v[56:59]

; #define LAS __attribute__((address_space(3)))
; __device__ __forceinline__ unsigned pk2(float lo, float hi) { const f32x2_t v = {lo, hi}; const bf16x2_t b = __builtin_convertvector(v, bf16x2_t); return __builtin_bit_cast(unsigned, b); }
; __device__ __forceinline__ bf16x8 cat8(const s16x4 a, const s16x4 b) { return __builtin_shufflevector(a, b, 0, 1, 2, 3, 4, 5, 6, 7); }
; __device__ __forceinline__ void hgrn_scan(const Params& p, LAS unsigned char* lds, int chain) {
;     ...
;             bf16* orow = O + (long)hg_row(dir, b, 64 * c) * WA;
; #pragma unroll
;             for (int I = 0; I < 4; ++I) {
;                 f32x4 o = (f32x4){0.f, 0.f, 0.f, 0.f};
; #pragma unroll
;                 for (int ks = 0; ks < 4; ++ks) {
;                     const LAS unsigned char* ap = bb + SB_QD + (32 * ks + 4 * g + qq) * HP + (16 * I + 4 * pp) * 2;
;                     o = __builtin_amdgcn_mfma_f32_16x16x32_bf16(sb[ks], cat8(lds_tr(ap), lds_tr(ap + 16 * HP)), o, 0, 0, 0);
;                 }
; #pragma unroll
;                 for (int sp = 0; sp < 2; ++sp) {
;                     if (2 * sp > I) break;
;                     const LAS unsigned char* pr = bb + SB_P + (16 * I + li) * PP + (32 * sp + 4 * g) * 2;
;                     const u32x2 lo = *(const LAS u32x2*)pr; u32x2 hi = (u32x2){0u, 0u};
;                     if (2 * sp + 1 <= I) hi = *(const LAS u32x2*)(pr + 32);
;                     o = __builtin_amdgcn_mfma_f32_16x16x32_bf16(vf[sp], cat8u(lo, hi), o, 0, 0, 0);
;                 }
;                 { u32x2 w; w.x = pk2(o.x, o.y); w.y = pk2(o.z, o.w); *(u32x2*)(orow + (long)(16 * I + li) * ost) = w; }
;             }
.LBB0_424:
	s_andn2_b64 vcc, exec, s[16:17]
	s_cbranch_vccnz .LBB0_426
	ds_read_b64_tr_b16 v[176:177], v162 offset:2560
	ds_read_b64_tr_b16 v[174:175], v162
	ds_read_b64_tr_b16 v[178:179], v162 offset:32
	ds_read_b64_tr_b16 v[182:183], v162 offset:64
	ds_read_b64_tr_b16 v[186:187], v162 offset:96
	ds_read_b64_tr_b16 v[180:181], v162 offset:2592
	ds_read_b64_tr_b16 v[184:185], v162 offset:2624
	ds_read_b64_tr_b16 v[188:189], v162 offset:2656
	s_waitcnt lgkmcnt(6)
	v_mfma_f32_16x16x32_bf16 v[174:177], v[104:107], v[174:177], 0
	ds_read_b64_tr_b16 v[192:193], v162 offset:7680
	ds_read_b64_tr_b16 v[190:191], v162 offset:5120
	ds_read_b64_tr_b16 v[194:195], v162 offset:5152
	ds_read_b64_tr_b16 v[198:199], v162 offset:5184
	ds_read_b64_tr_b16 v[202:203], v162 offset:5216
	ds_read_b64_tr_b16 v[196:197], v162 offset:7712
	ds_read_b64_tr_b16 v[200:201], v162 offset:7744
	ds_read_b64_tr_b16 v[204:205], v162 offset:7776
	s_waitcnt lgkmcnt(10)
	v_mfma_f32_16x16x32_bf16 v[178:181], v[104:107], v[178:181], 0
	s_waitcnt lgkmcnt(6)
	v_mfma_f32_16x16x32_bf16 v[174:177], v[108:111], v[190:193], v[174:177]
	ds_read_b64_tr_b16 v[192:193], v162 offset:12800
	ds_read_b64_tr_b16 v[190:191], v162 offset:10240
	ds_read_b64_tr_b16 v[206:207], v162 offset:10272
	ds_read_b64_tr_b16 v[210:211], v162 offset:10304
	ds_read_b64_tr_b16 v[214:215], v162 offset:10336
	ds_read_b64_tr_b16 v[208:209], v162 offset:12832
	ds_read_b64_tr_b16 v[212:213], v162 offset:12864
	ds_read_b64_tr_b16 v[216:217], v162 offset:12896
	s_waitcnt lgkmcnt(10)
	v_mfma_f32_16x16x32_bf16 v[178:181], v[108:111], v[194:197], v[178:181]
	v_add_u32_e32 v165, 0x800, v163
	v_mov_b32_e32 v220, v115
	v_mfma_f32_16x16x32_bf16 v[182:185], v[104:107], v[182:185], 0
	v_mov_b32_e32 v221, v115
	s_add_i32 s12, s22, 64
	s_sub_i32 s18, s20, 64
	s_waitcnt lgkmcnt(6)
	v_mfma_f32_16x16x32_bf16 v[174:177], v[166:169], v[190:193], v[174:177]
	ds_read_b64_tr_b16 v[192:193], v162 offset:17920
	ds_read_b64 v[218:219], v163
	ds_read_b64_tr_b16 v[190:191], v162 offset:15360
	ds_read_b64_tr_b16 v[222:223], v162 offset:15392
	ds_read_b64_tr_b16 v[226:227], v162 offset:15424
	ds_read_b64_tr_b16 v[230:231], v162 offset:15456
	ds_read_b64_tr_b16 v[224:225], v162 offset:17952
	ds_read_b64_tr_b16 v[228:229], v162 offset:17984
	ds_read_b64_tr_b16 v[232:233], v162 offset:18016
	s_and_b64 s[16:17], s[6:7], exec
	s_cselect_b32 s12, s12, s18
	s_waitcnt lgkmcnt(11)
	v_mfma_f32_16x16x32_bf16 v[178:181], v[166:169], v[206:209], v[178:181]
	s_lshl_b64 s[16:17], s[12:13], 11
	v_mfma_f32_16x16x32_bf16 v[182:185], v[108:111], v[198:201], v[182:185]
	s_waitcnt lgkmcnt(6)
	v_mfma_f32_16x16x32_bf16 v[174:177], v[170:173], v[190:193], v[174:177]
	ds_read2_b64 v[192:195], v165 offset0:32 offset1:36
	v_add_u32_e32 v165, 0x1000, v163
	ds_read_b64 v[190:191], v163 offset:4672
	s_waitcnt lgkmcnt(4)
	v_mfma_f32_16x16x32_bf16 v[178:181], v[170:173], v[222:225], v[178:181]
	v_mfma_f32_16x16x32_bf16 v[182:185], v[166:169], v[210:213], v[182:185]
	v_mfma_f32_16x16x32_bf16 v[104:107], v[104:107], v[186:189], 0
	s_waitcnt lgkmcnt(1)
	v_mfma_f32_16x16x32_bf16 v[178:181], v[100:103], v[192:195], v[178:181]
	ds_read2_b64 v[192:195], v165 offset0:64 offset1:68
	v_add_u32_e32 v165, 0x1800, v163
	v_mfma_f32_16x16x32_bf16 v[182:185], v[170:173], v[226:229], v[182:185]
	v_mfma_f32_16x16x32_bf16 v[104:107], v[108:111], v[202:205], v[104:107]
	ds_read2_b64 v[108:111], v165 offset0:96 offset1:100
	s_waitcnt lgkmcnt(1)
	v_mfma_f32_16x16x32_bf16 v[182:185], v[100:103], v[192:195], v[182:185]
	v_mov_b32_e32 v192, v115
	v_mov_b32_e32 v193, v115
	v_mfma_f32_16x16x32_bf16 v[104:107], v[166:169], v[214:217], v[104:107]
	v_mfma_f32_16x16x32_bf16 v[174:177], v[100:103], v[218:221], v[174:177]
	v_mfma_f32_16x16x32_bf16 v[182:185], v[96:99], v[190:193], v[182:185]
	v_lshl_add_u64 v[190:191], v[118:119], 0, s[16:17]
	s_nop 5
	v_cvt_pk_bf16_f32 v174, v174, v175
	v_cvt_pk_bf16_f32 v175, v176, v177
	v_mfma_f32_16x16x32_bf16 v[104:107], v[170:173], v[230:233], v[104:107]
	v_lshl_add_u64 v[176:177], v[120:121], 1, v[190:191]
	global_store_dwordx2 v[176:177], v[174:175], off
	v_cvt_pk_bf16_f32 v174, v178, v179
	v_cvt_pk_bf16_f32 v175, v180, v181
	v_lshl_add_u64 v[166:167], v[122:123], 1, v[190:191]
	global_store_dwordx2 v[166:167], v[174:175], off
	ds_read2_b64 v[166:169], v165 offset0:104 offset1:108
	s_waitcnt lgkmcnt(1)
	v_mfma_f32_16x16x32_bf16 v[104:107], v[100:103], v[108:111], v[104:107]
	v_cvt_pk_bf16_f32 v170, v182, v183
	v_cvt_pk_bf16_f32 v171, v184, v185
	v_lshl_add_u64 v[108:109], v[124:125], 1, v[190:191]
	s_waitcnt lgkmcnt(0)
	v_mfma_f32_16x16x32_bf16 v[104:107], v[96:99], v[166:169], v[104:107]
	global_store_dwordx2 v[108:109], v[170:171], off
	s_nop 6
	v_cvt_pk_bf16_f32 v104, v104, v105
	v_cvt_pk_bf16_f32 v105, v106, v107
	v_lshl_add_u64 v[106:107], v[126:127], 1, v[190:191]
	global_store_dwordx2 v[106:107], v[104:105], off
; #define LAS __attribute__((address_space(3)))
; __device__ __forceinline__ void hgrn_scan(const Params& p, LAS unsigned char* lds, int chain) {
;     ...
;             for (int ks = 0; ks < 4; ++ks) sb[ks] = pack_p(S[2 * ks], S[2 * ks + 1]);
;     ...
; #pragma unroll
;         for (int blk = 0; blk < 8; ++blk) {
;             const f32x4 d4 = *(const LAS f32x4*)(bb + SB_D + (16 * blk + 4 * g) * 4);
;             f32x4 s = S[blk] * d4;
; #pragma unroll
;             for (int sp = 0; sp < 2; ++sp) {
;                 const LAS unsigned char* kp = bb + SB_KD + (16 * blk + li) * HPK + (32 * sp + 4 * g) * 2;
;                 s = __builtin_amdgcn_mfma_f32_16x16x32_bf16(cat8u(*(const LAS u32x2*)kp, *(const LAS u32x2*)(kp + 32)), vf[sp], s, 0, 0, 0);
;             }
;             S[blk] = s;
;         }
;         if (c + 1 < NCH) HS_STORE(c + 1, (uu + 1) & 1);
.LBB0_426:
	v_add_u32_e32 v165, v153, v144
	v_add_u32_e32 v174, 0x1d200, v143
	ds_read_b128 v[180:183], v174 offset:0
	ds_read_b64 v[184:185], v165 offset:0
	ds_read_b64 v[186:187], v165 offset:32
	ds_read_b64 v[188:189], v165 offset:64
	ds_read_b64 v[190:191], v165 offset:96
	ds_read_b128 v[192:195], v174 offset:64
	ds_read_b64 v[196:197], v165 offset:2176
	ds_read_b64 v[198:199], v165 offset:2208
	ds_read_b64 v[200:201], v165 offset:2240
	ds_read_b64 v[202:203], v165 offset:2272
	s_waitcnt lgkmcnt(10)
	ds_read_b128 v[204:207], v174 offset:128
	ds_read_b64 v[208:209], v165 offset:4352
	ds_read_b64 v[210:211], v165 offset:4384
	ds_read_b64 v[212:213], v165 offset:4416
	ds_read_b64 v[214:215], v165 offset:4448
	s_waitcnt lgkmcnt(5)
	v_pk_mul_f32 v[76:77], v[76:77], v[180:181]
	v_pk_mul_f32 v[78:79], v[78:79], v[182:183]
	v_pk_mul_f32 v[92:93], v[92:93], v[192:193]
	v_pk_mul_f32 v[94:95], v[94:95], v[194:195]
	v_mfma_f32_16x16x32_bf16 v[76:79], v[184:187], v[100:103], v[76:79]
	s_nop 0
	v_mfma_f32_16x16x32_bf16 v[92:95], v[196:199], v[100:103], v[92:95]
	v_mfma_f32_16x16x32_bf16 v[76:79], v[188:191], v[96:99], v[76:79]
	v_mfma_f32_16x16x32_bf16 v[92:95], v[200:203], v[96:99], v[92:95]
	ds_read_b128 v[180:183], v174 offset:192
	ds_read_b64 v[184:185], v165 offset:6528
	ds_read_b64 v[186:187], v165 offset:6560
	ds_read_b64 v[188:189], v165 offset:6592
	ds_read_b64 v[190:191], v165 offset:6624
	ds_read_b128 v[192:195], v174 offset:256
	ds_read_b64 v[196:197], v165 offset:8704
	ds_read_b64 v[198:199], v165 offset:8736
	ds_read_b64 v[200:201], v165 offset:8768
	ds_read_b64 v[202:203], v165 offset:8800
	s_waitcnt lgkmcnt(5)
	v_pk_mul_f32 v[80:81], v[80:81], v[204:205]
	v_pk_mul_f32 v[82:83], v[82:83], v[206:207]
	v_pk_mul_f32 v[88:89], v[88:89], v[180:181]
	v_pk_mul_f32 v[90:91], v[90:91], v[182:183]
	v_mfma_f32_16x16x32_bf16 v[80:83], v[208:211], v[100:103], v[80:83]
	s_nop 0
	v_mfma_f32_16x16x32_bf16 v[88:91], v[184:187], v[100:103], v[88:91]
	v_mfma_f32_16x16x32_bf16 v[80:83], v[212:215], v[96:99], v[80:83]
	v_mfma_f32_16x16x32_bf16 v[88:91], v[188:191], v[96:99], v[88:91]
	ds_read_b128 v[204:207], v174 offset:320
	ds_read_b64 v[208:209], v165 offset:10880
	ds_read_b64 v[210:211], v165 offset:10912
	ds_read_b64 v[212:213], v165 offset:10944
	ds_read_b64 v[214:215], v165 offset:10976
	ds_read_b128 v[180:183], v174 offset:384
	ds_read_b64 v[184:185], v165 offset:13056
	ds_read_b64 v[186:187], v165 offset:13088
	ds_read_b64 v[188:189], v165 offset:13120
	ds_read_b64 v[190:191], v165 offset:13152
	s_waitcnt lgkmcnt(5)
	v_pk_mul_f32 v[72:73], v[72:73], v[192:193]
	v_pk_mul_f32 v[74:75], v[74:75], v[194:195]
	v_pk_mul_f32 v[84:85], v[84:85], v[204:205]
	v_pk_mul_f32 v[86:87], v[86:87], v[206:207]
	v_mfma_f32_16x16x32_bf16 v[72:75], v[196:199], v[100:103], v[72:75]
	s_nop 0
	v_mfma_f32_16x16x32_bf16 v[84:87], v[208:211], v[100:103], v[84:87]
	v_mfma_f32_16x16x32_bf16 v[72:75], v[200:203], v[96:99], v[72:75]
	v_mfma_f32_16x16x32_bf16 v[84:87], v[212:215], v[96:99], v[84:87]
	ds_read_b128 v[192:195], v174 offset:448
	ds_read_b64 v[196:197], v165 offset:15232
	ds_read_b64 v[198:199], v165 offset:15264
	ds_read_b64 v[200:201], v165 offset:15296
	ds_read_b64 v[202:203], v165 offset:15328
	s_waitcnt lgkmcnt(0)
	v_pk_mul_f32 v[64:65], v[64:65], v[180:181]
	v_pk_mul_f32 v[66:67], v[66:67], v[182:183]
	v_pk_mul_f32 v[68:69], v[68:69], v[192:193]
	v_pk_mul_f32 v[70:71], v[70:71], v[194:195]
	v_mfma_f32_16x16x32_bf16 v[64:67], v[184:187], v[100:103], v[64:67]
	s_nop 0
	v_mfma_f32_16x16x32_bf16 v[68:71], v[196:199], v[100:103], v[68:71]
	v_mfma_f32_16x16x32_bf16 v[64:67], v[188:191], v[96:99], v[64:67]
	v_mfma_f32_16x16x32_bf16 v[68:71], v[200:203], v[96:99], v[68:71]
	v_cvt_pk_bf16_f32 v104, v76, v77
	v_cvt_pk_bf16_f32 v105, v78, v79
	v_cvt_pk_bf16_f32 v106, v92, v93
	v_cvt_pk_bf16_f32 v107, v94, v95
	v_cvt_pk_bf16_f32 v108, v80, v81
	v_cvt_pk_bf16_f32 v109, v82, v83
	v_cvt_pk_bf16_f32 v110, v88, v89
	v_cvt_pk_bf16_f32 v111, v90, v91
	v_cvt_pk_bf16_f32 v166, v72, v73
	v_cvt_pk_bf16_f32 v167, v74, v75
	v_cvt_pk_bf16_f32 v168, v84, v85
	v_cvt_pk_bf16_f32 v169, v86, v87
	v_cvt_pk_bf16_f32 v170, v64, v65
	v_cvt_pk_bf16_f32 v171, v66, v67
	v_cvt_pk_bf16_f32 v172, v68, v69
	v_cvt_pk_bf16_f32 v173, v70, v71
	s_add_i32 s12, s30, 3
	s_cmp_gt_u32 s12, 34
	s_cbranch_scc1 .LBB0_432
	s_cmp_eq_u32 s14, 0
	s_cbranch_scc1 .LBB0_429
	v_add_u32_e32 v96, v154, v113
	ds_write_b128 v96, v[48:51]
	ds_write_b128 v96, v[52:55] offset:10240
	ds_write_b128 v164, v[60:63] offset:40960
